# final output stores in the last GEMM epilogue also non-temporal (on top of the non-temporal residual stores in P5)
# baseline (speedup 1.0000x reference)
;     __device__ __forceinline__ void operator()(const f32x4 (&acc)[2][2][4][2], const Unit& u, int wr, int wc, int fr, int fq) const {
;     ...
;             for (int m = 0; m < 4; ++m) { const size_t off = (size_t)(row0 + ai * HALF + m * 16) * 2048 + col0;
; #pragma unroll
;                 for (int bj = 0; bj < 2; ++bj) { const f32x4 a0 = acc[ai][bj][m][0], a1 = acc[ai][bj][m][1];
;                     const f32x4 x0 = *(const f32x4*)(OUT + off + bj * HALF), x1 = *(const f32x4*)(OUT + off + bj * HALF + 4); const u32x4 pl = *(const u32x4*)(PLE + off + bj * HALF);
;                     f32x4 o0, o1;
; #pragma unroll
;                     for (int e = 0; e < 2; ++e) { const float pl0 = __uint_as_float(pl[e] << 16), pl1 = __uint_as_float(pl[e] & 0xffff0000u), ph0 = __uint_as_float(pl[2 + e] << 16), ph1 = __uint_as_float(pl[2 + e] & 0xffff0000u);
;                         o0[2 * e] = x0[2 * e] + pl0 * __builtin_amdgcn_rcpf(1.f + __expf(-a0[2 * e])); o0[2 * e + 1] = x0[2 * e + 1] + pl1 * __builtin_amdgcn_rcpf(1.f + __expf(-a0[2 * e + 1]));
;                         o1[2 * e] = x1[2 * e] + ph0 * __builtin_amdgcn_rcpf(1.f + __expf(-a1[2 * e])); o1[2 * e + 1] = x1[2 * e + 1] + ph1 * __builtin_amdgcn_rcpf(1.f + __expf(-a1[2 * e + 1])); }
;                     *(f32x4*)(OUT + off + bj * HALF) = o0; *(f32x4*)(OUT + off + bj * HALF + 4) = o1; asm volatile("" ::: "memory"); } }
.LBB0_867:
	s_lshl_b32 s2, s28, 8
	v_mbcnt_lo_u32_b32 v144, -1, 0
	v_mbcnt_hi_u32_b32 v144, -1, v144
	s_add_i32 s2, s2, s41
	v_and_or_b32 v148, v144, 15, s2
	s_lshl_b32 s2, s48, 8
	v_ashrrev_i32_e32 v144, 1, v144
	s_or_b32 s2, s2, s42
	v_and_b32_e32 v144, -8, v144
	v_add_u32_e32 v146, s2, v144
	v_ashrrev_i32_e32 v149, 31, v148
	v_ashrrev_i32_e32 v147, 31, v146
	v_lshlrev_b64 v[144:145], 11, v[148:149]
	v_lshl_add_u64 v[144:145], v[144:145], 0, v[146:147]
	v_lshl_add_u64 v[166:167], v[144:145], 1, s[6:7]
	global_load_dwordx4 v[154:157], v[166:167], off
	v_lshl_add_u64 v[168:169], v[144:145], 2, s[88:89]
	global_load_dwordx4 v[158:161], v[168:169], off
	global_load_dwordx4 v[162:165], v[168:169], off offset:16
	v_mul_f32_e32 v124, 0xbfb8aa3b, v124
	v_mul_f32_e32 v125, 0xbfb8aa3b, v125
	v_mul_f32_e32 v120, 0xbfb8aa3b, v120
	v_mul_f32_e32 v121, 0xbfb8aa3b, v121
	v_mul_f32_e32 v126, 0xbfb8aa3b, v126
	v_mul_f32_e32 v127, 0xbfb8aa3b, v127
	v_mul_f32_e32 v122, 0xbfb8aa3b, v122
	v_mul_f32_e32 v123, 0xbfb8aa3b, v123
	v_exp_f32_e32 v124, v124
	v_exp_f32_e32 v125, v125
	v_exp_f32_e32 v120, v120
	v_exp_f32_e32 v121, v121
	v_exp_f32_e32 v126, v126
	v_exp_f32_e32 v127, v127
	v_exp_f32_e32 v122, v122
	v_exp_f32_e32 v123, v123
	v_add_f32_e32 v124, 1.0, v124
	v_add_f32_e32 v125, 1.0, v125
	v_add_f32_e32 v149, 1.0, v120
	v_add_f32_e32 v170, 1.0, v121
	v_add_f32_e32 v126, 1.0, v126
	v_add_f32_e32 v127, 1.0, v127
	v_add_f32_e32 v171, 1.0, v122
	v_add_f32_e32 v172, 1.0, v123
	v_rcp_f32_e32 v120, v124
	v_rcp_f32_e32 v121, v125
	v_rcp_f32_e32 v122, v149
	v_rcp_f32_e32 v123, v170
	v_rcp_f32_e32 v126, v126
	v_rcp_f32_e32 v127, v127
	v_rcp_f32_e32 v170, v171
	v_rcp_f32_e32 v171, v172
	v_mul_f32_e32 v116, 0xbfb8aa3b, v116
	v_mul_f32_e32 v117, 0xbfb8aa3b, v117
	v_mul_f32_e32 v118, 0xbfb8aa3b, v118
	v_mul_f32_e32 v119, 0xbfb8aa3b, v119
	v_mul_f32_e32 v112, 0xbfb8aa3b, v112
	v_mul_f32_e32 v113, 0xbfb8aa3b, v113
	v_mul_f32_e32 v114, 0xbfb8aa3b, v114
	v_mul_f32_e32 v115, 0xbfb8aa3b, v115
	v_exp_f32_e32 v116, v116
	v_exp_f32_e32 v117, v117
	v_exp_f32_e32 v118, v118
	v_exp_f32_e32 v119, v119
	v_exp_f32_e32 v149, v112
	v_exp_f32_e32 v114, v114
	v_exp_f32_e32 v115, v115
	v_add_f32_e32 v116, 1.0, v116
	v_add_f32_e32 v117, 1.0, v117
	v_add_f32_e32 v118, 1.0, v118
	v_add_f32_e32 v119, 1.0, v119
	v_or_b32_e32 v112, 16, v148
	v_add_f32_e32 v149, 1.0, v149
	v_rcp_f32_e32 v118, v118
	v_rcp_f32_e32 v119, v119
	v_mul_f32_e32 v108, 0xbfb8aa3b, v108
	v_mul_f32_e32 v109, 0xbfb8aa3b, v109
	v_mul_f32_e32 v104, 0xbfb8aa3b, v104
	v_mul_f32_e32 v105, 0xbfb8aa3b, v105
	v_mul_f32_e32 v110, 0xbfb8aa3b, v110
	v_mul_f32_e32 v111, 0xbfb8aa3b, v111
	v_mul_f32_e32 v106, 0xbfb8aa3b, v106
	v_mul_f32_e32 v107, 0xbfb8aa3b, v107
	v_exp_f32_e32 v108, v108
	v_exp_f32_e32 v109, v109
	v_exp_f32_e32 v104, v104
	v_exp_f32_e32 v105, v105
	v_exp_f32_e32 v110, v110
	v_exp_f32_e32 v111, v111
	v_exp_f32_e32 v106, v106
	v_exp_f32_e32 v107, v107
	v_add_f32_e32 v108, 1.0, v108
	v_add_f32_e32 v109, 1.0, v109
	v_add_f32_e32 v110, 1.0, v110
	v_add_f32_e32 v111, 1.0, v111
	v_rcp_f32_e32 v110, v110
	v_rcp_f32_e32 v111, v111
	s_waitcnt vmcnt(0)
	v_lshlrev_b32_e32 v124, 16, v154
	v_and_b32_e32 v125, 0xffff0000, v154
	v_lshlrev_b32_e32 v172, 16, v156
	v_and_b32_e32 v173, 0xffff0000, v156
	v_lshlrev_b32_e32 v154, 16, v155
	v_and_b32_e32 v155, 0xffff0000, v155
	v_lshlrev_b32_e32 v156, 16, v157
	v_and_b32_e32 v157, 0xffff0000, v157
	v_pk_fma_f32 v[120:121], v[120:121], v[124:125], v[158:159]
	v_pk_fma_f32 v[124:125], v[122:123], v[172:173], v[162:163]
	v_pk_fma_f32 v[122:123], v[126:127], v[154:155], v[160:161]
	v_pk_fma_f32 v[126:127], v[170:171], v[156:157], v[164:165]
	global_store_dwordx4 v[168:169], v[120:123], off nt
	global_store_dwordx4 v[168:169], v[124:127], off offset:16 nt
	global_load_dwordx4 v[120:123], v[166:167], off offset:256
	global_load_dwordx4 v[124:127], v[168:169], off offset:512
	global_load_dwordx4 v[154:157], v[168:169], off offset:528
	v_exp_f32_e32 v158, v113
	v_add_f32_e32 v159, 1.0, v114
	v_add_f32_e32 v160, 1.0, v115
	v_rcp_f32_e32 v114, v116
	v_add_f32_e32 v158, 1.0, v158
	v_rcp_f32_e32 v115, v117
	v_ashrrev_i32_e32 v113, 31, v112
	v_rcp_f32_e32 v116, v149
	v_rcp_f32_e32 v117, v158
	v_rcp_f32_e32 v158, v159
	v_rcp_f32_e32 v159, v160
	v_lshlrev_b64 v[112:113], 11, v[112:113]
	v_lshl_add_u64 v[160:161], v[112:113], 0, v[146:147]
	v_lshl_add_u64 v[162:163], v[160:161], 1, s[6:7]
	v_add_f32_e32 v149, 1.0, v106
	v_mul_f32_e32 v100, 0xbfb8aa3b, v100
	v_mul_f32_e32 v101, 0xbfb8aa3b, v101
	v_mul_f32_e32 v102, 0xbfb8aa3b, v102
	v_mul_f32_e32 v103, 0xbfb8aa3b, v103
	v_mul_f32_e32 v96, 0xbfb8aa3b, v96
	v_mul_f32_e32 v97, 0xbfb8aa3b, v97
	v_mul_f32_e32 v98, 0xbfb8aa3b, v98
	v_mul_f32_e32 v99, 0xbfb8aa3b, v99
	v_exp_f32_e32 v100, v100
	v_exp_f32_e32 v101, v101
	v_exp_f32_e32 v102, v102
	v_exp_f32_e32 v103, v103
	v_exp_f32_e32 v98, v98
	v_exp_f32_e32 v99, v99
	v_add_f32_e32 v100, 1.0, v100
	v_add_f32_e32 v101, 1.0, v101
	v_add_f32_e32 v102, 1.0, v102
	v_add_f32_e32 v103, 1.0, v103
	v_rcp_f32_e32 v102, v102
	v_rcp_f32_e32 v103, v103
	v_mul_f32_e32 v92, 0xbfb8aa3b, v92
	v_mul_f32_e32 v93, 0xbfb8aa3b, v93
	v_mul_f32_e32 v88, 0xbfb8aa3b, v88
	v_mul_f32_e32 v89, 0xbfb8aa3b, v89
	v_mul_f32_e32 v94, 0xbfb8aa3b, v94
	v_mul_f32_e32 v95, 0xbfb8aa3b, v95
	v_mul_f32_e32 v90, 0xbfb8aa3b, v90
	v_mul_f32_e32 v91, 0xbfb8aa3b, v91
	v_exp_f32_e32 v92, v92
	v_exp_f32_e32 v93, v93
	v_exp_f32_e32 v88, v88
	v_exp_f32_e32 v89, v89
	v_exp_f32_e32 v94, v94
	v_exp_f32_e32 v95, v95
	v_exp_f32_e32 v90, v90
	v_exp_f32_e32 v91, v91
	v_add_f32_e32 v92, 1.0, v92
	v_add_f32_e32 v93, 1.0, v93
	v_add_f32_e32 v94, 1.0, v94
	v_add_f32_e32 v95, 1.0, v95
	v_rcp_f32_e32 v94, v94
	v_rcp_f32_e32 v95, v95
	v_mul_f32_e32 v84, 0xbfb8aa3b, v84
	v_mul_f32_e32 v85, 0xbfb8aa3b, v85
	v_mul_f32_e32 v86, 0xbfb8aa3b, v86
	v_mul_f32_e32 v87, 0xbfb8aa3b, v87
	v_mul_f32_e32 v80, 0xbfb8aa3b, v80
	v_mul_f32_e32 v81, 0xbfb8aa3b, v81
	v_mul_f32_e32 v82, 0xbfb8aa3b, v82
	v_mul_f32_e32 v83, 0xbfb8aa3b, v83
	v_exp_f32_e32 v84, v84
	v_exp_f32_e32 v85, v85
	v_exp_f32_e32 v86, v86
	v_exp_f32_e32 v87, v87
	v_exp_f32_e32 v82, v82
	v_exp_f32_e32 v83, v83
	v_add_f32_e32 v84, 1.0, v84
	v_add_f32_e32 v85, 1.0, v85
	v_add_f32_e32 v86, 1.0, v86
	v_add_f32_e32 v87, 1.0, v87
	v_rcp_f32_e32 v86, v86
	v_rcp_f32_e32 v87, v87
	s_waitcnt vmcnt(2)
;     __device__ __forceinline__ void operator()(const f32x4 (&acc)[2][2][4][2], const Unit& u, int wr, int wc, int fr, int fq) const {
;     ...
;             for (int m = 0; m < 4; ++m) { const size_t off = (size_t)(row0 + ai * HALF + m * 16) * 2048 + col0;
; #pragma unroll
;                 for (int bj = 0; bj < 2; ++bj) { const f32x4 a0 = acc[ai][bj][m][0], a1 = acc[ai][bj][m][1];
;                     const f32x4 x0 = *(const f32x4*)(OUT + off + bj * HALF), x1 = *(const f32x4*)(OUT + off + bj * HALF + 4); const u32x4 pl = *(const u32x4*)(PLE + off + bj * HALF);
;                     f32x4 o0, o1;
; #pragma unroll
;                     for (int e = 0; e < 2; ++e) { const float pl0 = __uint_as_float(pl[e] << 16), pl1 = __uint_as_float(pl[e] & 0xffff0000u), ph0 = __uint_as_float(pl[2 + e] << 16), ph1 = __uint_as_float(pl[2 + e] & 0xffff0000u);
;                         o0[2 * e] = x0[2 * e] + pl0 * __builtin_amdgcn_rcpf(1.f + __expf(-a0[2 * e])); o0[2 * e + 1] = x0[2 * e + 1] + pl1 * __builtin_amdgcn_rcpf(1.f + __expf(-a0[2 * e + 1]));
;                         o1[2 * e] = x1[2 * e] + ph0 * __builtin_amdgcn_rcpf(1.f + __expf(-a1[2 * e])); o1[2 * e + 1] = x1[2 * e + 1] + ph1 * __builtin_amdgcn_rcpf(1.f + __expf(-a1[2 * e + 1])); }
;                     *(f32x4*)(OUT + off + bj * HALF) = o0; *(f32x4*)(OUT + off + bj * HALF + 4) = o1; asm volatile("" ::: "memory"); } }
	v_lshlrev_b32_e32 v112, 16, v120
	v_and_b32_e32 v113, 0xffff0000, v120
	v_lshlrev_b32_e32 v120, 16, v121
	v_and_b32_e32 v121, 0xffff0000, v121
	v_lshlrev_b32_e32 v164, 16, v122
	v_and_b32_e32 v165, 0xffff0000, v122
	v_lshlrev_b32_e32 v122, 16, v123
	v_and_b32_e32 v123, 0xffff0000, v123
	s_waitcnt vmcnt(1)
	v_pk_fma_f32 v[112:113], v[114:115], v[112:113], v[124:125]
	v_pk_fma_f32 v[114:115], v[118:119], v[120:121], v[126:127]
	s_waitcnt vmcnt(0)
	v_pk_fma_f32 v[116:117], v[116:117], v[164:165], v[154:155]
	v_pk_fma_f32 v[118:119], v[158:159], v[122:123], v[156:157]
	global_store_dwordx4 v[168:169], v[112:115], off offset:512 nt
	global_store_dwordx4 v[168:169], v[116:119], off offset:528 nt
	global_load_dwordx4 v[112:115], v[162:163], off
	v_lshl_add_u64 v[124:125], v[160:161], 2, s[88:89]
	global_load_dwordx4 v[116:119], v[124:125], off
	global_load_dwordx4 v[120:123], v[124:125], off offset:16
	v_add_f32_e32 v126, 1.0, v104
	v_add_f32_e32 v127, 1.0, v105
	v_add_f32_e32 v154, 1.0, v107
	v_rcp_f32_e32 v104, v108
	v_rcp_f32_e32 v105, v109
	v_rcp_f32_e32 v106, v126
	v_rcp_f32_e32 v107, v127
	v_rcp_f32_e32 v126, v149
	v_rcp_f32_e32 v127, v154
	v_mul_f32_e32 v76, 0xbfb8aa3b, v76
	v_mul_f32_e32 v77, 0xbfb8aa3b, v77
	v_mul_f32_e32 v72, 0xbfb8aa3b, v72
	v_mul_f32_e32 v73, 0xbfb8aa3b, v73
	v_mul_f32_e32 v78, 0xbfb8aa3b, v78
	v_mul_f32_e32 v79, 0xbfb8aa3b, v79
	v_mul_f32_e32 v74, 0xbfb8aa3b, v74
	v_mul_f32_e32 v75, 0xbfb8aa3b, v75
	v_exp_f32_e32 v76, v76
	v_exp_f32_e32 v77, v77
	v_exp_f32_e32 v72, v72
	v_exp_f32_e32 v73, v73
	v_exp_f32_e32 v78, v78
	v_exp_f32_e32 v79, v79
	v_exp_f32_e32 v74, v74
	v_exp_f32_e32 v75, v75
	v_add_f32_e32 v76, 1.0, v76
	v_add_f32_e32 v77, 1.0, v77
	v_add_f32_e32 v78, 1.0, v78
	v_add_f32_e32 v79, 1.0, v79
	v_rcp_f32_e32 v78, v78
	v_rcp_f32_e32 v79, v79
	v_mul_f32_e32 v68, 0xbfb8aa3b, v68
	v_mul_f32_e32 v69, 0xbfb8aa3b, v69
	v_mul_f32_e32 v64, 0xbfb8aa3b, v64
	v_mul_f32_e32 v65, 0xbfb8aa3b, v65
	v_mul_f32_e32 v70, 0xbfb8aa3b, v70
	v_mul_f32_e32 v71, 0xbfb8aa3b, v71
	v_mul_f32_e32 v66, 0xbfb8aa3b, v66
	v_mul_f32_e32 v67, 0xbfb8aa3b, v67
	v_exp_f32_e32 v68, v68
	v_exp_f32_e32 v69, v69
	v_exp_f32_e32 v64, v64
	v_exp_f32_e32 v65, v65
	v_exp_f32_e32 v70, v70
	v_exp_f32_e32 v71, v71
	v_exp_f32_e32 v66, v66
	v_exp_f32_e32 v67, v67
	v_add_f32_e32 v68, 1.0, v68
	v_add_f32_e32 v69, 1.0, v69
	v_add_f32_e32 v70, 1.0, v70
	v_add_f32_e32 v71, 1.0, v71
	v_rcp_f32_e32 v70, v70
	v_rcp_f32_e32 v71, v71
	v_mul_f32_e32 v60, 0xbfb8aa3b, v60
	v_mul_f32_e32 v61, 0xbfb8aa3b, v61
	v_mul_f32_e32 v56, 0xbfb8aa3b, v56
	v_mul_f32_e32 v57, 0xbfb8aa3b, v57
	v_mul_f32_e32 v62, 0xbfb8aa3b, v62
	v_mul_f32_e32 v63, 0xbfb8aa3b, v63
	v_mul_f32_e32 v58, 0xbfb8aa3b, v58
	v_mul_f32_e32 v59, 0xbfb8aa3b, v59
	v_exp_f32_e32 v60, v60
	v_exp_f32_e32 v61, v61
	v_exp_f32_e32 v56, v56
	v_exp_f32_e32 v57, v57
	v_exp_f32_e32 v62, v62
	v_exp_f32_e32 v63, v63
	v_exp_f32_e32 v58, v58
	v_exp_f32_e32 v59, v59
	v_add_f32_e32 v60, 1.0, v60
	v_add_f32_e32 v61, 1.0, v61
	v_add_f32_e32 v62, 1.0, v62
	v_add_f32_e32 v63, 1.0, v63
	v_rcp_f32_e32 v62, v62
	v_rcp_f32_e32 v63, v63
	v_mul_f32_e32 v52, 0xbfb8aa3b, v52
	v_mul_f32_e32 v53, 0xbfb8aa3b, v53
	s_waitcnt vmcnt(2)
	v_lshlrev_b32_e32 v108, 16, v112
	v_and_b32_e32 v109, 0xffff0000, v112
	v_lshlrev_b32_e32 v154, 16, v114
	v_and_b32_e32 v155, 0xffff0000, v114
	v_lshlrev_b32_e32 v112, 16, v113
	v_and_b32_e32 v113, 0xffff0000, v113
	v_lshlrev_b32_e32 v114, 16, v115
	v_and_b32_e32 v115, 0xffff0000, v115
	s_waitcnt vmcnt(1)
	v_pk_fma_f32 v[104:105], v[104:105], v[108:109], v[116:117]
	s_waitcnt vmcnt(0)
	v_pk_fma_f32 v[108:109], v[106:107], v[154:155], v[120:121]
	v_pk_fma_f32 v[106:107], v[110:111], v[112:113], v[118:119]
	v_pk_fma_f32 v[110:111], v[126:127], v[114:115], v[122:123]
	global_store_dwordx4 v[124:125], v[104:107], off nt
	global_store_dwordx4 v[124:125], v[108:111], off offset:16 nt
	global_load_dwordx4 v[104:107], v[162:163], off offset:256
	global_load_dwordx4 v[108:111], v[124:125], off offset:512
	global_load_dwordx4 v[112:115], v[124:125], off offset:528
	v_exp_f32_e32 v116, v96
	v_exp_f32_e32 v117, v97
	v_or_b32_e32 v96, 32, v148
	v_add_f32_e32 v118, 1.0, v98
	v_add_f32_e32 v116, 1.0, v116
	v_add_f32_e32 v117, 1.0, v117
	v_add_f32_e32 v119, 1.0, v99
	v_rcp_f32_e32 v98, v100
	v_rcp_f32_e32 v99, v101
	v_ashrrev_i32_e32 v97, 31, v96
	v_rcp_f32_e32 v100, v116
	v_rcp_f32_e32 v101, v117
	v_rcp_f32_e32 v116, v118
	v_rcp_f32_e32 v117, v119
	v_lshlrev_b64 v[96:97], 11, v[96:97]
	v_lshl_add_u64 v[118:119], v[96:97], 0, v[146:147]
	v_lshl_add_u64 v[120:121], v[118:119], 1, s[6:7]
	v_mul_f32_e32 v48, 0xbfb8aa3b, v48
	v_mul_f32_e32 v49, 0xbfb8aa3b, v49
	v_mul_f32_e32 v54, 0xbfb8aa3b, v54
	v_mul_f32_e32 v55, 0xbfb8aa3b, v55
	v_mul_f32_e32 v50, 0xbfb8aa3b, v50
	v_mul_f32_e32 v51, 0xbfb8aa3b, v51
	v_exp_f32_e32 v52, v52
	v_exp_f32_e32 v53, v53
	v_exp_f32_e32 v48, v48
	v_exp_f32_e32 v49, v49
	v_exp_f32_e32 v54, v54
	v_exp_f32_e32 v55, v55
	v_exp_f32_e32 v50, v50
	v_exp_f32_e32 v51, v51
	v_add_f32_e32 v52, 1.0, v52
	v_add_f32_e32 v53, 1.0, v53
	v_add_f32_e32 v54, 1.0, v54
	v_add_f32_e32 v55, 1.0, v55
	v_rcp_f32_e32 v54, v54
	v_rcp_f32_e32 v55, v55
	v_mul_f32_e32 v44, 0xbfb8aa3b, v44
	v_mul_f32_e32 v45, 0xbfb8aa3b, v45
	v_mul_f32_e32 v40, 0xbfb8aa3b, v40
	v_mul_f32_e32 v41, 0xbfb8aa3b, v41
	v_mul_f32_e32 v46, 0xbfb8aa3b, v46
	v_mul_f32_e32 v47, 0xbfb8aa3b, v47
	v_mul_f32_e32 v42, 0xbfb8aa3b, v42
	v_mul_f32_e32 v43, 0xbfb8aa3b, v43
	v_exp_f32_e32 v44, v44
	v_exp_f32_e32 v45, v45
	v_exp_f32_e32 v40, v40
	v_exp_f32_e32 v41, v41
	v_exp_f32_e32 v46, v46
	v_exp_f32_e32 v47, v47
	v_exp_f32_e32 v42, v42
	v_exp_f32_e32 v43, v43
	v_add_f32_e32 v44, 1.0, v44
	v_add_f32_e32 v45, 1.0, v45
	v_add_f32_e32 v46, 1.0, v46
	v_add_f32_e32 v47, 1.0, v47
	v_rcp_f32_e32 v46, v46
	v_rcp_f32_e32 v47, v47
	v_mul_f32_e32 v36, 0xbfb8aa3b, v36
	v_mul_f32_e32 v37, 0xbfb8aa3b, v37
	v_mul_f32_e32 v32, 0xbfb8aa3b, v32
	v_mul_f32_e32 v33, 0xbfb8aa3b, v33
	v_mul_f32_e32 v38, 0xbfb8aa3b, v38
	v_mul_f32_e32 v39, 0xbfb8aa3b, v39
	v_mul_f32_e32 v34, 0xbfb8aa3b, v34
	v_mul_f32_e32 v35, 0xbfb8aa3b, v35
	v_exp_f32_e32 v36, v36
	v_exp_f32_e32 v37, v37
	v_exp_f32_e32 v32, v32
	v_exp_f32_e32 v33, v33
	v_exp_f32_e32 v38, v38
	v_exp_f32_e32 v39, v39
	v_exp_f32_e32 v34, v34
	v_exp_f32_e32 v35, v35
	v_add_f32_e32 v36, 1.0, v36
	v_add_f32_e32 v37, 1.0, v37
	s_waitcnt vmcnt(2)
;     __device__ __forceinline__ void operator()(const f32x4 (&acc)[2][2][4][2], const Unit& u, int wr, int wc, int fr, int fq) const {
;     ...
;                 for (int bj = 0; bj < 2; ++bj) { const f32x4 a0 = acc[ai][bj][m][0], a1 = acc[ai][bj][m][1];
;                     const f32x4 x0 = *(const f32x4*)(OUT + off + bj * HALF), x1 = *(const f32x4*)(OUT + off + bj * HALF + 4); const u32x4 pl = *(const u32x4*)(PLE + off + bj * HALF);
;                     f32x4 o0, o1;
; #pragma unroll
;                     for (int e = 0; e < 2; ++e) { const float pl0 = __uint_as_float(pl[e] << 16), pl1 = __uint_as_float(pl[e] & 0xffff0000u), ph0 = __uint_as_float(pl[2 + e] << 16), ph1 = __uint_as_float(pl[2 + e] & 0xffff0000u);
;                         o0[2 * e] = x0[2 * e] + pl0 * __builtin_amdgcn_rcpf(1.f + __expf(-a0[2 * e])); o0[2 * e + 1] = x0[2 * e + 1] + pl1 * __builtin_amdgcn_rcpf(1.f + __expf(-a0[2 * e + 1]));
;                         o1[2 * e] = x1[2 * e] + ph0 * __builtin_amdgcn_rcpf(1.f + __expf(-a1[2 * e])); o1[2 * e + 1] = x1[2 * e + 1] + ph1 * __builtin_amdgcn_rcpf(1.f + __expf(-a1[2 * e + 1])); }
;                     *(f32x4*)(OUT + off + bj * HALF) = o0; *(f32x4*)(OUT + off + bj * HALF + 4) = o1; asm volatile("" ::: "memory"); } }
	v_lshlrev_b32_e32 v96, 16, v104
	v_and_b32_e32 v97, 0xffff0000, v104
	v_lshlrev_b32_e32 v104, 16, v105
	v_and_b32_e32 v105, 0xffff0000, v105
	v_lshlrev_b32_e32 v122, 16, v106
	v_and_b32_e32 v123, 0xffff0000, v106
	v_lshlrev_b32_e32 v106, 16, v107
	v_and_b32_e32 v107, 0xffff0000, v107
	s_waitcnt vmcnt(1)
	v_pk_fma_f32 v[96:97], v[98:99], v[96:97], v[108:109]
	v_pk_fma_f32 v[98:99], v[102:103], v[104:105], v[110:111]
	s_waitcnt vmcnt(0)
	v_pk_fma_f32 v[100:101], v[100:101], v[122:123], v[112:113]
	v_pk_fma_f32 v[102:103], v[116:117], v[106:107], v[114:115]
	global_store_dwordx4 v[124:125], v[96:99], off offset:512 nt
	global_store_dwordx4 v[124:125], v[100:103], off offset:528 nt
	global_load_dwordx4 v[96:99], v[120:121], off
	v_lshl_add_u64 v[108:109], v[118:119], 2, s[88:89]
	global_load_dwordx4 v[100:103], v[108:109], off
	global_load_dwordx4 v[104:107], v[108:109], off offset:16
	v_add_f32_e32 v110, 1.0, v88
	v_add_f32_e32 v111, 1.0, v89
	v_add_f32_e32 v112, 1.0, v90
	v_add_f32_e32 v113, 1.0, v91
	v_rcp_f32_e32 v88, v92
	v_rcp_f32_e32 v89, v93
	v_rcp_f32_e32 v90, v110
	v_rcp_f32_e32 v91, v111
	v_rcp_f32_e32 v110, v112
	v_rcp_f32_e32 v111, v113
	v_add_f32_e32 v38, 1.0, v38
	v_add_f32_e32 v39, 1.0, v39
	v_rcp_f32_e32 v38, v38
	v_rcp_f32_e32 v39, v39
	v_mul_f32_e32 v28, 0xbfb8aa3b, v28
	v_mul_f32_e32 v29, 0xbfb8aa3b, v29
	v_mul_f32_e32 v24, 0xbfb8aa3b, v24
	v_mul_f32_e32 v25, 0xbfb8aa3b, v25
	v_mul_f32_e32 v30, 0xbfb8aa3b, v30
	v_mul_f32_e32 v31, 0xbfb8aa3b, v31
	v_mul_f32_e32 v26, 0xbfb8aa3b, v26
	v_mul_f32_e32 v27, 0xbfb8aa3b, v27
	v_exp_f32_e32 v28, v28
	v_exp_f32_e32 v29, v29
	v_exp_f32_e32 v24, v24
	v_exp_f32_e32 v25, v25
	v_exp_f32_e32 v30, v30
	v_exp_f32_e32 v31, v31
	v_exp_f32_e32 v26, v26
	v_exp_f32_e32 v27, v27
	v_add_f32_e32 v28, 1.0, v28
	v_add_f32_e32 v29, 1.0, v29
	v_add_f32_e32 v30, 1.0, v30
	v_add_f32_e32 v31, 1.0, v31
	v_rcp_f32_e32 v30, v30
	v_rcp_f32_e32 v31, v31
	v_mul_f32_e32 v20, 0xbfb8aa3b, v20
	v_mul_f32_e32 v21, 0xbfb8aa3b, v21
	v_mul_f32_e32 v16, 0xbfb8aa3b, v16
	v_mul_f32_e32 v17, 0xbfb8aa3b, v17
	v_mul_f32_e32 v22, 0xbfb8aa3b, v22
	v_mul_f32_e32 v23, 0xbfb8aa3b, v23
	v_mul_f32_e32 v18, 0xbfb8aa3b, v18
	v_mul_f32_e32 v19, 0xbfb8aa3b, v19
	v_exp_f32_e32 v20, v20
	v_exp_f32_e32 v21, v21
	v_exp_f32_e32 v16, v16
	v_exp_f32_e32 v17, v17
	v_exp_f32_e32 v22, v22
	v_exp_f32_e32 v23, v23
	v_exp_f32_e32 v18, v18
	v_exp_f32_e32 v19, v19
	v_add_f32_e32 v20, 1.0, v20
	v_add_f32_e32 v21, 1.0, v21
	v_add_f32_e32 v22, 1.0, v22
	v_add_f32_e32 v23, 1.0, v23
	v_rcp_f32_e32 v22, v22
	v_rcp_f32_e32 v23, v23
	v_mul_f32_e32 v12, 0xbfb8aa3b, v12
	v_mul_f32_e32 v13, 0xbfb8aa3b, v13
	v_mul_f32_e32 v8, 0xbfb8aa3b, v8
	v_mul_f32_e32 v9, 0xbfb8aa3b, v9
	v_mul_f32_e32 v14, 0xbfb8aa3b, v14
	v_mul_f32_e32 v15, 0xbfb8aa3b, v15
	v_mul_f32_e32 v10, 0xbfb8aa3b, v10
	v_mul_f32_e32 v11, 0xbfb8aa3b, v11
	v_exp_f32_e32 v12, v12
	v_exp_f32_e32 v13, v13
	v_exp_f32_e32 v8, v8
	v_exp_f32_e32 v9, v9
	v_exp_f32_e32 v14, v14
	v_exp_f32_e32 v15, v15
	v_exp_f32_e32 v10, v10
	v_exp_f32_e32 v11, v11
	v_add_f32_e32 v12, 1.0, v12
	v_add_f32_e32 v13, 1.0, v13
	v_add_f32_e32 v14, 1.0, v14
	s_waitcnt vmcnt(2)
	v_lshlrev_b32_e32 v92, 16, v96
	v_and_b32_e32 v93, 0xffff0000, v96
	v_lshlrev_b32_e32 v112, 16, v98
	v_and_b32_e32 v113, 0xffff0000, v98
	v_lshlrev_b32_e32 v96, 16, v97
	v_and_b32_e32 v97, 0xffff0000, v97
	v_lshlrev_b32_e32 v98, 16, v99
	v_and_b32_e32 v99, 0xffff0000, v99
	s_waitcnt vmcnt(1)
	v_pk_fma_f32 v[88:89], v[88:89], v[92:93], v[100:101]
	s_waitcnt vmcnt(0)
	v_pk_fma_f32 v[92:93], v[90:91], v[112:113], v[104:105]
	v_pk_fma_f32 v[90:91], v[94:95], v[96:97], v[102:103]
	v_pk_fma_f32 v[94:95], v[110:111], v[98:99], v[106:107]
	global_store_dwordx4 v[108:109], v[88:91], off nt
	global_store_dwordx4 v[108:109], v[92:95], off offset:16 nt
	global_load_dwordx4 v[88:91], v[120:121], off offset:256
	global_load_dwordx4 v[92:95], v[108:109], off offset:512
	global_load_dwordx4 v[96:99], v[108:109], off offset:528
	v_exp_f32_e32 v100, v80
	v_exp_f32_e32 v101, v81
	v_or_b32_e32 v80, 48, v148
	v_add_f32_e32 v102, 1.0, v82
	v_add_f32_e32 v100, 1.0, v100
	v_add_f32_e32 v101, 1.0, v101
	v_add_f32_e32 v103, 1.0, v83
	v_rcp_f32_e32 v82, v84
	v_rcp_f32_e32 v83, v85
	v_ashrrev_i32_e32 v81, 31, v80
	v_rcp_f32_e32 v84, v100
	v_rcp_f32_e32 v85, v101
	v_rcp_f32_e32 v100, v102
	v_rcp_f32_e32 v101, v103
	v_lshlrev_b64 v[80:81], 11, v[80:81]
	v_lshl_add_u64 v[102:103], v[80:81], 0, v[146:147]
	v_lshl_add_u64 v[104:105], v[102:103], 1, s[6:7]
	v_add_f32_e32 v15, 1.0, v15
	v_rcp_f32_e32 v14, v14
	v_rcp_f32_e32 v15, v15
	v_mul_f32_e32 v4, 0xbfb8aa3b, v4
	v_mul_f32_e32 v5, 0xbfb8aa3b, v5
	v_mul_f32_e32 v0, 0xbfb8aa3b, v0
	v_mul_f32_e32 v1, 0xbfb8aa3b, v1
	v_mul_f32_e32 v6, 0xbfb8aa3b, v6
	v_mul_f32_e32 v7, 0xbfb8aa3b, v7
	v_mul_f32_e32 v2, 0xbfb8aa3b, v2
	v_mul_f32_e32 v3, 0xbfb8aa3b, v3
	v_exp_f32_e32 v4, v4
	v_exp_f32_e32 v5, v5
	v_exp_f32_e32 v0, v0
	v_exp_f32_e32 v1, v1
	v_exp_f32_e32 v6, v6
	v_exp_f32_e32 v7, v7
	v_exp_f32_e32 v2, v2
	v_exp_f32_e32 v3, v3
	v_add_f32_e32 v4, 1.0, v4
	v_add_f32_e32 v5, 1.0, v5
	v_add_f32_e32 v6, 1.0, v6
	v_add_f32_e32 v7, 1.0, v7
	v_rcp_f32_e32 v6, v6
	v_rcp_f32_e32 v7, v7
	s_andn2_b64 vcc, exec, s[0:1]
	s_mov_b64 s[0:1], -1
	s_waitcnt vmcnt(2)
	v_lshlrev_b32_e32 v80, 16, v88
	v_and_b32_e32 v81, 0xffff0000, v88
	v_lshlrev_b32_e32 v88, 16, v89
	v_and_b32_e32 v89, 0xffff0000, v89
	v_lshlrev_b32_e32 v106, 16, v90
	v_and_b32_e32 v107, 0xffff0000, v90
	v_lshlrev_b32_e32 v90, 16, v91
	v_and_b32_e32 v91, 0xffff0000, v91
	s_waitcnt vmcnt(1)
	v_pk_fma_f32 v[80:81], v[82:83], v[80:81], v[92:93]
	v_pk_fma_f32 v[82:83], v[86:87], v[88:89], v[94:95]
	s_waitcnt vmcnt(0)
;     __device__ __forceinline__ void operator()(const f32x4 (&acc)[2][2][4][2], const Unit& u, int wr, int wc, int fr, int fq) const {
;     ...
;                 for (int bj = 0; bj < 2; ++bj) { const f32x4 a0 = acc[ai][bj][m][0], a1 = acc[ai][bj][m][1];
;                     const f32x4 x0 = *(const f32x4*)(OUT + off + bj * HALF), x1 = *(const f32x4*)(OUT + off + bj * HALF + 4); const u32x4 pl = *(const u32x4*)(PLE + off + bj * HALF);
;                     f32x4 o0, o1;
; #pragma unroll
;                     for (int e = 0; e < 2; ++e) { const float pl0 = __uint_as_float(pl[e] << 16), pl1 = __uint_as_float(pl[e] & 0xffff0000u), ph0 = __uint_as_float(pl[2 + e] << 16), ph1 = __uint_as_float(pl[2 + e] & 0xffff0000u);
;                         o0[2 * e] = x0[2 * e] + pl0 * __builtin_amdgcn_rcpf(1.f + __expf(-a0[2 * e])); o0[2 * e + 1] = x0[2 * e + 1] + pl1 * __builtin_amdgcn_rcpf(1.f + __expf(-a0[2 * e + 1]));
;                         o1[2 * e] = x1[2 * e] + ph0 * __builtin_amdgcn_rcpf(1.f + __expf(-a1[2 * e])); o1[2 * e + 1] = x1[2 * e + 1] + ph1 * __builtin_amdgcn_rcpf(1.f + __expf(-a1[2 * e + 1])); }
;                     *(f32x4*)(OUT + off + bj * HALF) = o0; *(f32x4*)(OUT + off + bj * HALF + 4) = o1; asm volatile("" ::: "memory"); } }
	v_pk_fma_f32 v[84:85], v[84:85], v[106:107], v[96:97]
	v_pk_fma_f32 v[86:87], v[100:101], v[90:91], v[98:99]
	global_store_dwordx4 v[108:109], v[80:83], off offset:512 nt
	global_store_dwordx4 v[108:109], v[84:87], off offset:528 nt
	global_load_dwordx4 v[80:83], v[104:105], off
	v_lshl_add_u64 v[92:93], v[102:103], 2, s[88:89]
	global_load_dwordx4 v[84:87], v[92:93], off
	global_load_dwordx4 v[88:91], v[92:93], off offset:16
	v_add_f32_e32 v94, 1.0, v72
	v_add_f32_e32 v95, 1.0, v73
	v_add_f32_e32 v96, 1.0, v74
	v_add_f32_e32 v97, 1.0, v75
	v_rcp_f32_e32 v72, v76
	v_rcp_f32_e32 v73, v77
	v_rcp_f32_e32 v74, v94
	v_rcp_f32_e32 v75, v95
	v_rcp_f32_e32 v94, v96
	v_rcp_f32_e32 v95, v97
	s_waitcnt vmcnt(2)
	v_lshlrev_b32_e32 v76, 16, v80
	v_and_b32_e32 v77, 0xffff0000, v80
	v_lshlrev_b32_e32 v96, 16, v82
	v_and_b32_e32 v97, 0xffff0000, v82
	v_lshlrev_b32_e32 v80, 16, v81
	v_and_b32_e32 v81, 0xffff0000, v81
	v_lshlrev_b32_e32 v82, 16, v83
	v_and_b32_e32 v83, 0xffff0000, v83
	s_waitcnt vmcnt(1)
	v_pk_fma_f32 v[72:73], v[72:73], v[76:77], v[84:85]
	s_waitcnt vmcnt(0)
	v_pk_fma_f32 v[76:77], v[74:75], v[96:97], v[88:89]
	v_pk_fma_f32 v[74:75], v[78:79], v[80:81], v[86:87]
	v_pk_fma_f32 v[78:79], v[94:95], v[82:83], v[90:91]
	global_store_dwordx4 v[92:93], v[72:75], off nt
	global_store_dwordx4 v[92:93], v[76:79], off offset:16 nt
	global_load_dwordx4 v[72:75], v[104:105], off offset:256
	global_load_dwordx4 v[76:79], v[92:93], off offset:512
	global_load_dwordx4 v[80:83], v[92:93], off offset:528
	v_add_f32_e32 v84, 1.0, v64
	v_add_f32_e32 v85, 1.0, v65
	v_add_f32_e32 v86, 1.0, v66
	v_add_f32_e32 v87, 1.0, v67
	v_rcp_f32_e32 v64, v68
	v_rcp_f32_e32 v65, v69
	v_rcp_f32_e32 v66, v84
	v_rcp_f32_e32 v67, v85
	v_rcp_f32_e32 v84, v86
	v_rcp_f32_e32 v85, v87
	v_lshl_add_u64 v[86:87], v[144:145], 0, s[12:13]
	v_lshl_add_u64 v[88:89], v[86:87], 1, s[6:7]
	s_waitcnt vmcnt(2)
	v_lshlrev_b32_e32 v68, 16, v72
	v_and_b32_e32 v69, 0xffff0000, v72
	v_lshlrev_b32_e32 v90, 16, v74
	v_and_b32_e32 v91, 0xffff0000, v74
	v_lshlrev_b32_e32 v72, 16, v73
	v_and_b32_e32 v73, 0xffff0000, v73
	v_lshlrev_b32_e32 v74, 16, v75
	v_and_b32_e32 v75, 0xffff0000, v75
	s_waitcnt vmcnt(1)
	v_pk_fma_f32 v[64:65], v[64:65], v[68:69], v[76:77]
	s_waitcnt vmcnt(0)
	v_pk_fma_f32 v[68:69], v[66:67], v[90:91], v[80:81]
	v_pk_fma_f32 v[66:67], v[70:71], v[72:73], v[78:79]
	v_pk_fma_f32 v[70:71], v[84:85], v[74:75], v[82:83]
	global_store_dwordx4 v[92:93], v[64:67], off offset:512 nt
	global_store_dwordx4 v[92:93], v[68:71], off offset:528 nt
	global_load_dwordx4 v[64:67], v[88:89], off
	v_lshl_add_u64 v[76:77], v[86:87], 2, s[88:89]
	global_load_dwordx4 v[68:71], v[76:77], off
	global_load_dwordx4 v[72:75], v[76:77], off offset:16
	v_add_f32_e32 v78, 1.0, v56
	v_add_f32_e32 v79, 1.0, v57
	v_add_f32_e32 v80, 1.0, v58
	v_add_f32_e32 v81, 1.0, v59
	v_rcp_f32_e32 v56, v60
	v_rcp_f32_e32 v57, v61
	v_rcp_f32_e32 v58, v78
	v_rcp_f32_e32 v59, v79
	v_rcp_f32_e32 v78, v80
	v_rcp_f32_e32 v79, v81
	s_waitcnt vmcnt(2)
	v_lshlrev_b32_e32 v60, 16, v64
	v_and_b32_e32 v61, 0xffff0000, v64
	v_lshlrev_b32_e32 v80, 16, v66
	v_and_b32_e32 v81, 0xffff0000, v66
	v_lshlrev_b32_e32 v64, 16, v65
	v_and_b32_e32 v65, 0xffff0000, v65
	v_lshlrev_b32_e32 v66, 16, v67
	v_and_b32_e32 v67, 0xffff0000, v67
	s_waitcnt vmcnt(1)
	v_pk_fma_f32 v[56:57], v[56:57], v[60:61], v[68:69]
	s_waitcnt vmcnt(0)
	v_pk_fma_f32 v[60:61], v[58:59], v[80:81], v[72:73]
	v_pk_fma_f32 v[58:59], v[62:63], v[64:65], v[70:71]
	v_pk_fma_f32 v[62:63], v[78:79], v[66:67], v[74:75]
	global_store_dwordx4 v[76:77], v[56:59], off nt
	global_store_dwordx4 v[76:77], v[60:63], off offset:16 nt
	global_load_dwordx4 v[56:59], v[88:89], off offset:256
	global_load_dwordx4 v[60:63], v[76:77], off offset:512
	global_load_dwordx4 v[64:67], v[76:77], off offset:528
	v_add_f32_e32 v68, 1.0, v48
	v_add_f32_e32 v69, 1.0, v49
	v_add_f32_e32 v70, 1.0, v50
	v_add_f32_e32 v71, 1.0, v51
	v_rcp_f32_e32 v48, v52
	v_rcp_f32_e32 v49, v53
	v_rcp_f32_e32 v50, v68
	v_rcp_f32_e32 v51, v69
	v_rcp_f32_e32 v68, v70
	v_rcp_f32_e32 v69, v71
	v_lshl_add_u64 v[70:71], v[144:145], 0, s[14:15]
	v_lshl_add_u64 v[72:73], v[70:71], 1, s[6:7]
	s_waitcnt vmcnt(2)
	v_lshlrev_b32_e32 v52, 16, v56
	v_and_b32_e32 v53, 0xffff0000, v56
	v_lshlrev_b32_e32 v74, 16, v58
	v_and_b32_e32 v75, 0xffff0000, v58
	v_lshlrev_b32_e32 v56, 16, v57
	v_and_b32_e32 v57, 0xffff0000, v57
	v_lshlrev_b32_e32 v58, 16, v59
	v_and_b32_e32 v59, 0xffff0000, v59
	s_waitcnt vmcnt(1)
	v_pk_fma_f32 v[48:49], v[48:49], v[52:53], v[60:61]
	s_waitcnt vmcnt(0)
	v_pk_fma_f32 v[52:53], v[50:51], v[74:75], v[64:65]
	v_pk_fma_f32 v[50:51], v[54:55], v[56:57], v[62:63]
	v_pk_fma_f32 v[54:55], v[68:69], v[58:59], v[66:67]
	global_store_dwordx4 v[76:77], v[48:51], off offset:512 nt
	global_store_dwordx4 v[76:77], v[52:55], off offset:528 nt
	global_load_dwordx4 v[48:51], v[72:73], off
	v_lshl_add_u64 v[60:61], v[70:71], 2, s[88:89]
	global_load_dwordx4 v[52:55], v[60:61], off
	global_load_dwordx4 v[56:59], v[60:61], off offset:16
	v_add_f32_e32 v62, 1.0, v40
	v_add_f32_e32 v63, 1.0, v41
	v_add_f32_e32 v64, 1.0, v42
	v_add_f32_e32 v65, 1.0, v43
	v_rcp_f32_e32 v40, v44
	v_rcp_f32_e32 v41, v45
	v_rcp_f32_e32 v42, v62
	v_rcp_f32_e32 v43, v63
	v_rcp_f32_e32 v62, v64
	v_rcp_f32_e32 v63, v65
	s_waitcnt vmcnt(2)
	v_lshlrev_b32_e32 v44, 16, v48
	v_and_b32_e32 v45, 0xffff0000, v48
	v_lshlrev_b32_e32 v64, 16, v50
	v_and_b32_e32 v65, 0xffff0000, v50
	v_lshlrev_b32_e32 v48, 16, v49
	v_and_b32_e32 v49, 0xffff0000, v49
	v_lshlrev_b32_e32 v50, 16, v51
	v_and_b32_e32 v51, 0xffff0000, v51
	s_waitcnt vmcnt(1)
	v_pk_fma_f32 v[40:41], v[40:41], v[44:45], v[52:53]
	s_waitcnt vmcnt(0)
;     __device__ __forceinline__ void operator()(const f32x4 (&acc)[2][2][4][2], const Unit& u, int wr, int wc, int fr, int fq) const {
;     ...
;                 for (int bj = 0; bj < 2; ++bj) { const f32x4 a0 = acc[ai][bj][m][0], a1 = acc[ai][bj][m][1];
;                     const f32x4 x0 = *(const f32x4*)(OUT + off + bj * HALF), x1 = *(const f32x4*)(OUT + off + bj * HALF + 4); const u32x4 pl = *(const u32x4*)(PLE + off + bj * HALF);
;                     f32x4 o0, o1;
; #pragma unroll
;                     for (int e = 0; e < 2; ++e) { const float pl0 = __uint_as_float(pl[e] << 16), pl1 = __uint_as_float(pl[e] & 0xffff0000u), ph0 = __uint_as_float(pl[2 + e] << 16), ph1 = __uint_as_float(pl[2 + e] & 0xffff0000u);
;                         o0[2 * e] = x0[2 * e] + pl0 * __builtin_amdgcn_rcpf(1.f + __expf(-a0[2 * e])); o0[2 * e + 1] = x0[2 * e + 1] + pl1 * __builtin_amdgcn_rcpf(1.f + __expf(-a0[2 * e + 1]));
;                         o1[2 * e] = x1[2 * e] + ph0 * __builtin_amdgcn_rcpf(1.f + __expf(-a1[2 * e])); o1[2 * e + 1] = x1[2 * e + 1] + ph1 * __builtin_amdgcn_rcpf(1.f + __expf(-a1[2 * e + 1])); }
;                     *(f32x4*)(OUT + off + bj * HALF) = o0; *(f32x4*)(OUT + off + bj * HALF + 4) = o1; asm volatile("" ::: "memory"); } }
	v_pk_fma_f32 v[44:45], v[42:43], v[64:65], v[56:57]
	v_pk_fma_f32 v[42:43], v[46:47], v[48:49], v[54:55]
	v_pk_fma_f32 v[46:47], v[62:63], v[50:51], v[58:59]
	global_store_dwordx4 v[60:61], v[40:43], off nt
	global_store_dwordx4 v[60:61], v[44:47], off offset:16 nt
	global_load_dwordx4 v[40:43], v[72:73], off offset:256
	global_load_dwordx4 v[44:47], v[60:61], off offset:512
	global_load_dwordx4 v[48:51], v[60:61], off offset:528
	v_add_f32_e32 v52, 1.0, v32
	v_add_f32_e32 v53, 1.0, v33
	v_add_f32_e32 v54, 1.0, v34
	v_add_f32_e32 v55, 1.0, v35
	v_rcp_f32_e32 v32, v36
	v_rcp_f32_e32 v33, v37
	v_rcp_f32_e32 v34, v52
	v_rcp_f32_e32 v35, v53
	v_rcp_f32_e32 v52, v54
	v_rcp_f32_e32 v53, v55
	v_lshl_add_u64 v[54:55], v[144:145], 0, s[16:17]
	v_lshl_add_u64 v[56:57], v[54:55], 1, s[6:7]
	s_waitcnt vmcnt(2)
	v_lshlrev_b32_e32 v36, 16, v40
	v_and_b32_e32 v37, 0xffff0000, v40
	v_lshlrev_b32_e32 v58, 16, v42
	v_and_b32_e32 v59, 0xffff0000, v42
	v_lshlrev_b32_e32 v40, 16, v41
	v_and_b32_e32 v41, 0xffff0000, v41
	v_lshlrev_b32_e32 v42, 16, v43
	v_and_b32_e32 v43, 0xffff0000, v43
	s_waitcnt vmcnt(1)
	v_pk_fma_f32 v[32:33], v[32:33], v[36:37], v[44:45]
	s_waitcnt vmcnt(0)
	v_pk_fma_f32 v[36:37], v[34:35], v[58:59], v[48:49]
	v_pk_fma_f32 v[34:35], v[38:39], v[40:41], v[46:47]
	v_pk_fma_f32 v[38:39], v[52:53], v[42:43], v[50:51]
	global_store_dwordx4 v[60:61], v[32:35], off offset:512 nt
	global_store_dwordx4 v[60:61], v[36:39], off offset:528 nt
	global_load_dwordx4 v[32:35], v[56:57], off
	v_lshl_add_u64 v[44:45], v[54:55], 2, s[88:89]
	global_load_dwordx4 v[36:39], v[44:45], off
	global_load_dwordx4 v[40:43], v[44:45], off offset:16
	v_add_f32_e32 v46, 1.0, v24
	v_add_f32_e32 v47, 1.0, v25
	v_add_f32_e32 v48, 1.0, v26
	v_add_f32_e32 v49, 1.0, v27
	v_rcp_f32_e32 v24, v28
	v_rcp_f32_e32 v25, v29
	v_rcp_f32_e32 v26, v46
	v_rcp_f32_e32 v27, v47
	v_rcp_f32_e32 v46, v48
	v_rcp_f32_e32 v47, v49
	s_waitcnt vmcnt(2)
	v_lshlrev_b32_e32 v28, 16, v32
	v_and_b32_e32 v29, 0xffff0000, v32
	v_lshlrev_b32_e32 v48, 16, v34
	v_and_b32_e32 v49, 0xffff0000, v34
	v_lshlrev_b32_e32 v32, 16, v33
	v_and_b32_e32 v33, 0xffff0000, v33
	v_lshlrev_b32_e32 v34, 16, v35
	v_and_b32_e32 v35, 0xffff0000, v35
	s_waitcnt vmcnt(1)
	v_pk_fma_f32 v[24:25], v[24:25], v[28:29], v[36:37]
	s_waitcnt vmcnt(0)
	v_pk_fma_f32 v[28:29], v[26:27], v[48:49], v[40:41]
	v_pk_fma_f32 v[26:27], v[30:31], v[32:33], v[38:39]
	v_pk_fma_f32 v[30:31], v[46:47], v[34:35], v[42:43]
	global_store_dwordx4 v[44:45], v[24:27], off nt
	global_store_dwordx4 v[44:45], v[28:31], off offset:16 nt
	global_load_dwordx4 v[24:27], v[56:57], off offset:256
	global_load_dwordx4 v[28:31], v[44:45], off offset:512
	global_load_dwordx4 v[32:35], v[44:45], off offset:528
	v_add_f32_e32 v36, 1.0, v16
	v_add_f32_e32 v37, 1.0, v17
	v_add_f32_e32 v38, 1.0, v18
	v_add_f32_e32 v39, 1.0, v19
	v_rcp_f32_e32 v16, v20
	v_rcp_f32_e32 v17, v21
	v_rcp_f32_e32 v18, v36
	v_rcp_f32_e32 v19, v37
	v_rcp_f32_e32 v36, v38
	v_rcp_f32_e32 v37, v39
	v_lshl_add_u64 v[38:39], v[144:145], 0, s[18:19]
	v_lshl_add_u64 v[40:41], v[38:39], 1, s[6:7]
	s_waitcnt vmcnt(2)
	v_lshlrev_b32_e32 v20, 16, v24
	v_and_b32_e32 v21, 0xffff0000, v24
	v_lshlrev_b32_e32 v42, 16, v26
	v_and_b32_e32 v43, 0xffff0000, v26
	v_lshlrev_b32_e32 v24, 16, v25
	v_and_b32_e32 v25, 0xffff0000, v25
	v_lshlrev_b32_e32 v26, 16, v27
	v_and_b32_e32 v27, 0xffff0000, v27
	s_waitcnt vmcnt(1)
	v_pk_fma_f32 v[16:17], v[16:17], v[20:21], v[28:29]
	s_waitcnt vmcnt(0)
	v_pk_fma_f32 v[20:21], v[18:19], v[42:43], v[32:33]
	v_pk_fma_f32 v[18:19], v[22:23], v[24:25], v[30:31]
	v_pk_fma_f32 v[22:23], v[36:37], v[26:27], v[34:35]
	global_store_dwordx4 v[44:45], v[16:19], off offset:512 nt
	global_store_dwordx4 v[44:45], v[20:23], off offset:528 nt
	global_load_dwordx4 v[16:19], v[40:41], off
	v_lshl_add_u64 v[28:29], v[38:39], 2, s[88:89]
	global_load_dwordx4 v[20:23], v[28:29], off
	global_load_dwordx4 v[24:27], v[28:29], off offset:16
	v_add_f32_e32 v30, 1.0, v8
	v_add_f32_e32 v31, 1.0, v9
	v_add_f32_e32 v32, 1.0, v10
	v_add_f32_e32 v33, 1.0, v11
	v_rcp_f32_e32 v8, v12
	v_rcp_f32_e32 v9, v13
	v_rcp_f32_e32 v10, v30
	v_rcp_f32_e32 v11, v31
	v_rcp_f32_e32 v30, v32
	v_rcp_f32_e32 v31, v33
	s_waitcnt vmcnt(2)
	v_lshlrev_b32_e32 v12, 16, v16
	v_and_b32_e32 v13, 0xffff0000, v16
	v_lshlrev_b32_e32 v32, 16, v18
	v_and_b32_e32 v33, 0xffff0000, v18
	v_lshlrev_b32_e32 v16, 16, v17
	v_and_b32_e32 v17, 0xffff0000, v17
	v_lshlrev_b32_e32 v18, 16, v19
	v_and_b32_e32 v19, 0xffff0000, v19
	s_waitcnt vmcnt(1)
	v_pk_fma_f32 v[8:9], v[8:9], v[12:13], v[20:21]
	s_waitcnt vmcnt(0)
	v_pk_fma_f32 v[12:13], v[10:11], v[32:33], v[24:25]
	v_pk_fma_f32 v[10:11], v[14:15], v[16:17], v[22:23]
	v_pk_fma_f32 v[14:15], v[30:31], v[18:19], v[26:27]
	global_store_dwordx4 v[28:29], v[8:11], off nt
	global_store_dwordx4 v[28:29], v[12:15], off offset:16 nt
	global_load_dwordx4 v[8:11], v[40:41], off offset:256
	global_load_dwordx4 v[12:15], v[28:29], off offset:512
	global_load_dwordx4 v[16:19], v[28:29], off offset:528
	v_add_f32_e32 v20, 1.0, v0
	v_add_f32_e32 v21, 1.0, v1
	v_add_f32_e32 v22, 1.0, v2
	v_add_f32_e32 v23, 1.0, v3
	v_rcp_f32_e32 v0, v4
	v_rcp_f32_e32 v1, v5
	v_rcp_f32_e32 v2, v20
	v_rcp_f32_e32 v3, v21
	v_rcp_f32_e32 v20, v22
	v_rcp_f32_e32 v21, v23
	s_waitcnt vmcnt(2)
	v_lshlrev_b32_e32 v4, 16, v8
	v_and_b32_e32 v5, 0xffff0000, v8
	v_lshlrev_b32_e32 v22, 16, v10
	v_and_b32_e32 v23, 0xffff0000, v10
	v_lshlrev_b32_e32 v8, 16, v9
	v_and_b32_e32 v9, 0xffff0000, v9
	v_lshlrev_b32_e32 v10, 16, v11
	v_and_b32_e32 v11, 0xffff0000, v11
	s_waitcnt vmcnt(1)
	v_pk_fma_f32 v[0:1], v[0:1], v[4:5], v[12:13]
	s_waitcnt vmcnt(0)
	v_pk_fma_f32 v[4:5], v[2:3], v[22:23], v[16:17]
	v_pk_fma_f32 v[2:3], v[6:7], v[8:9], v[14:15]
	v_pk_fma_f32 v[6:7], v[20:21], v[10:11], v[18:19]
	global_store_dwordx4 v[28:29], v[0:3], off offset:512 nt
	global_store_dwordx4 v[28:29], v[4:7], off offset:528 nt
	s_cbranch_vccnz .LBB0_856
	s_andn2_b64 vcc, exec, s[4:5]
	s_cbranch_vccnz .LBB0_855
	s_barrier
	s_branch .LBB0_855
